# v21remap
# baseline (speedup 1.0000x reference)
.LBB0_414:
	v_readlane_b32 s0, v252, 31
	v_readlane_b32 s1, v252, 32
	v_readlane_b32 s80, v254, 35
	s_andn2_b64 vcc, exec, s[0:1]
	v_readlane_b32 s81, v254, 36
	v_readlane_b32 s82, v254, 37
	v_readlane_b32 s83, v254, 38
	v_readlane_b32 s84, v254, 39
	v_readlane_b32 s85, v254, 40
	v_readlane_b32 s86, v254, 41
	v_readlane_b32 s87, v254, 42
	v_readlane_b32 s88, v254, 43
	v_readlane_b32 s89, v254, 44
	v_readlane_b32 s90, v254, 45
	v_readlane_b32 s91, v254, 46
	v_readlane_b32 s92, v254, 47
	v_readlane_b32 s93, v254, 48
	v_readlane_b32 s94, v254, 49
	v_readlane_b32 s95, v254, 50
	s_cbranch_vccnz .LBB0_420
	v_readlane_b32 s0, v254, 23
	v_mov_b32_e32 v6, v167
	s_mov_b32 s26, 64
	v_mov_b32_e32 v0, s0
	ds_read_b32 v0, v0
	s_waitcnt lgkmcnt(0)
	v_readfirstlane_b32 s0, v0
	s_lshl_b32 s1, s0, 1
	s_ashr_i32 s9, s0, 6
	s_lshl_b32 s14, s0, 3
	s_bfe_u32 s17, s0, 0x30003
	s_and_b32 s0, s1, 12
	s_add_i32 s0, s0, s9
	s_and_b32 s1, s14, 8
	v_ashrrev_i32_e32 v7, 2, v6
	s_lshl_b32 s9, s0, 7
	s_or_b32 s1, s1, s17
	v_add_u32_e32 v0, s9, v7
	v_add_u32_e32 v0, 0x2000, v0
	s_lshl_b32 s1, s1, 7
	v_mad_i64_i32 v[2:3], s[38:39], v0, s6, 0
	v_add_u32_e32 v0, s1, v7
	v_mad_i64_i32 v[4:5], s[38:39], v0, s6, 0
	v_lshlrev_b32_e32 v0, 5, v6
	v_lshl_add_u64 v[4:5], v[4:5], 1, s[44:45]
	v_lshrrev_b32_e32 v60, 1, v0
	v_and_b32_e32 v60, 0x10, v60
	v_and_b32_e32 v0, 0x40, v0
	v_or_b32_e32 v0, v0, v60
	v_lshl_add_u64 v[2:3], v[2:3], 1, s[22:23]
	v_lshl_add_u64 v[52:53], v[4:5], 0, v[0:1]
	v_lshl_add_u64 v[50:51], v[2:3], 0, v[0:1]
	global_load_dwordx4 v[34:37], v[52:53], off offset:32
	global_load_dwordx4 v[38:41], v[52:53], off
	global_load_dwordx4 v[42:45], v[50:51], off offset:32
	global_load_dwordx4 v[46:49], v[50:51], off
	s_movk_i32 s6, 0xa0
	v_mul_lo_u32 v2, v7, s6
	v_add3_u32 v57, 0, v0, v2
	v_lshrrev_b32_e32 v0, 1, v6
	v_and_b32_e32 v55, 15, v6
	v_and_b32_e32 v56, 0xffffffc0, v7
	v_and_b32_e32 v0, 0x60, v0
	v_bfe_u32 v54, v6, 4, 2
	v_or_b32_e32 v2, v56, v55
	v_or_b32_e32 v4, v0, v55
	v_lshl_add_u32 v3, v54, 4, 0
	v_mul_lo_u32 v5, v2, s6
	v_mul_u32_u24_e32 v4, 0xa0, v4
	v_mov_b32_e32 v2, 0
	s_mov_b32 s6, 0
	v_add_u32_e32 v58, v3, v5
	v_add_u32_e32 v59, v3, v4
	v_mov_b32_e32 v3, v2
	v_mov_b32_e32 v4, v2
	v_mov_b32_e32 v5, v2
	v_mov_b32_e32 v18, v2
	v_mov_b32_e32 v19, v2
	v_mov_b32_e32 v20, v2
	v_mov_b32_e32 v21, v2
	v_mov_b32_e32 v6, v2
	v_mov_b32_e32 v7, v2
	v_mov_b32_e32 v8, v2
	v_mov_b32_e32 v9, v2
	v_mov_b32_e32 v22, v2
	v_mov_b32_e32 v23, v2
	v_mov_b32_e32 v24, v2
	v_mov_b32_e32 v25, v2
	v_mov_b32_e32 v10, v2
	v_mov_b32_e32 v11, v2
	v_mov_b32_e32 v12, v2
	v_mov_b32_e32 v13, v2
	v_mov_b32_e32 v26, v2
	v_mov_b32_e32 v27, v2
	v_mov_b32_e32 v28, v2
	v_mov_b32_e32 v29, v2
	v_mov_b32_e32 v14, v2
	v_mov_b32_e32 v15, v2
	v_mov_b32_e32 v16, v2
	v_mov_b32_e32 v17, v2
	v_mov_b32_e32 v30, v2
	v_mov_b32_e32 v31, v2
	v_mov_b32_e32 v32, v2
	v_mov_b32_e32 v33, v2
	s_branch .LBB0_417
.LBB0_417:
	s_mov_b32 s22, 0x80
	s_mov_b32 s23, 0
	v_lshl_add_u64 v[124:125], v[50:51], 0, s[22:23]
	v_lshl_add_u64 v[126:127], v[52:53], 0, s[22:23]
	global_load_dwordx4 v[84:87], v[124:125], off
	global_load_dwordx4 v[80:83], v[124:125], off offset:32
	global_load_dwordx4 v[76:79], v[126:127], off
	global_load_dwordx4 v[72:75], v[126:127], off offset:32
	s_waitcnt vmcnt(4) lgkmcnt(0)
	s_barrier
	ds_write_b128 v57, v[46:49]
	ds_write_b128 v57, v[42:45] offset:32
	ds_write_b128 v57, v[38:41] offset:20480
	ds_write_b128 v57, v[34:37] offset:20512
	s_waitcnt lgkmcnt(0)
	s_mov_b32 s22, 0x100
	v_lshl_add_u64 v[124:125], v[50:51], 0, s[22:23]
	v_lshl_add_u64 v[126:127], v[52:53], 0, s[22:23]
	global_load_dwordx4 v[46:49], v[124:125], off
	global_load_dwordx4 v[42:45], v[124:125], off offset:32
	global_load_dwordx4 v[38:41], v[126:127], off
	global_load_dwordx4 v[34:37], v[126:127], off offset:32
	s_barrier
	s_mov_b32 s6, 0
	s_waitcnt vmcnt(4)
	ds_write_b128 v57, v[84:87] offset:40960
	ds_write_b128 v57, v[80:83] offset:40992
	ds_write_b128 v57, v[76:79] offset:61440
	ds_write_b128 v57, v[72:75] offset:61472
	ds_read_b128 v[60:63], v59 offset:20480
	ds_read_b128 v[64:67], v58
	ds_read_b128 v[68:71], v59 offset:23040
	ds_read_b128 v[88:91], v58 offset:2560
	ds_read_b128 v[92:95], v58 offset:5120
	ds_read_b128 v[96:99], v58 offset:7680
	ds_read_b128 v[100:103], v59 offset:20544
	ds_read_b128 v[104:107], v58 offset:64
	ds_read_b128 v[108:111], v59 offset:23104
	ds_read_b128 v[112:115], v58 offset:2624
	ds_read_b128 v[116:119], v58 offset:5184
	ds_read_b128 v[120:123], v58 offset:7744
	s_add_i32 s14, s6, 3
	s_add_i32 s22, s64, -1
	s_min_u32 s14, s14, s22
	s_lshl_b32 s22, s14, 7
	s_waitcnt lgkmcnt(12)
	v_lshl_add_u64 v[124:125], v[50:51], 0, s[22:23]
	v_lshl_add_u64 v[126:127], v[52:53], 0, s[22:23]
	global_load_dwordx4 v[84:87], v[124:125], off
	global_load_dwordx4 v[80:83], v[124:125], off offset:32
	global_load_dwordx4 v[76:79], v[126:127], off
	global_load_dwordx4 v[72:75], v[126:127], off offset:32
	s_waitcnt lgkmcnt(0)
	s_barrier
.Lsrt_loop:
	s_waitcnt vmcnt(4)
	ds_write_b128 v57, v[46:49]
	ds_write_b128 v57, v[42:45] offset:32
	ds_write_b128 v57, v[38:41] offset:20480
	ds_write_b128 v57, v[34:37] offset:20512
	ds_read_b128 v[176:179], v59 offset:61440
	ds_read_b128 v[180:183], v58 offset:40960
	ds_read_b128 v[184:187], v59 offset:64000
	ds_read_b128 v[188:191], v58 offset:43520
	ds_read_b128 v[192:195], v58 offset:46080
	ds_read_b128 v[196:199], v58 offset:48640
	ds_read_b128 v[200:203], v59 offset:61504
	ds_read_b128 v[204:207], v58 offset:41024
	ds_read_b128 v[208:211], v59 offset:64064
	ds_read_b128 v[224:227], v58 offset:43584
	ds_read_b128 v[228:231], v58 offset:46144
	ds_read_b128 v[232:235], v58 offset:48704
	s_add_i32 s14, s6, 4
	s_add_i32 s22, s64, -1
	s_min_u32 s14, s14, s22
	s_lshl_b32 s22, s14, 7
	v_mfma_f32_16x16x32_bf16 v[30:33], v[60:63], v[64:67], v[30:33]
	v_mfma_f32_16x16x32_bf16 v[14:17], v[68:71], v[64:67], v[14:17]
	v_mfma_f32_16x16x32_bf16 v[26:29], v[60:63], v[88:91], v[26:29]
	v_mfma_f32_16x16x32_bf16 v[10:13], v[68:71], v[88:91], v[10:13]
	v_mfma_f32_16x16x32_bf16 v[22:25], v[60:63], v[92:95], v[22:25]
	v_mfma_f32_16x16x32_bf16 v[6:9], v[68:71], v[92:95], v[6:9]
	v_mfma_f32_16x16x32_bf16 v[18:21], v[60:63], v[96:99], v[18:21]
	v_mfma_f32_16x16x32_bf16 v[2:5], v[68:71], v[96:99], v[2:5]
	s_waitcnt lgkmcnt(12)
	v_lshl_add_u64 v[124:125], v[50:51], 0, s[22:23]
	v_lshl_add_u64 v[126:127], v[52:53], 0, s[22:23]
	global_load_dwordx4 v[46:49], v[124:125], off
	global_load_dwordx4 v[42:45], v[124:125], off offset:32
	global_load_dwordx4 v[38:41], v[126:127], off
	global_load_dwordx4 v[34:37], v[126:127], off offset:32
	v_mfma_f32_16x16x32_bf16 v[30:33], v[100:103], v[104:107], v[30:33]
	v_mfma_f32_16x16x32_bf16 v[14:17], v[108:111], v[104:107], v[14:17]
	v_mfma_f32_16x16x32_bf16 v[26:29], v[100:103], v[112:115], v[26:29]
	v_mfma_f32_16x16x32_bf16 v[10:13], v[108:111], v[112:115], v[10:13]
	v_mfma_f32_16x16x32_bf16 v[22:25], v[100:103], v[116:119], v[22:25]
	v_mfma_f32_16x16x32_bf16 v[6:9], v[108:111], v[116:119], v[6:9]
	v_mfma_f32_16x16x32_bf16 v[18:21], v[100:103], v[120:123], v[18:21]
	v_mfma_f32_16x16x32_bf16 v[2:5], v[108:111], v[120:123], v[2:5]
	s_waitcnt lgkmcnt(0)
	s_barrier
	s_waitcnt vmcnt(4)
	ds_write_b128 v57, v[84:87] offset:40960
	ds_write_b128 v57, v[80:83] offset:40992
	ds_write_b128 v57, v[76:79] offset:61440
	ds_write_b128 v57, v[72:75] offset:61472
	ds_read_b128 v[60:63], v59 offset:20480
	ds_read_b128 v[64:67], v58
	ds_read_b128 v[68:71], v59 offset:23040
	ds_read_b128 v[88:91], v58 offset:2560
	ds_read_b128 v[92:95], v58 offset:5120
	ds_read_b128 v[96:99], v58 offset:7680
	ds_read_b128 v[100:103], v59 offset:20544
	ds_read_b128 v[104:107], v58 offset:64
	ds_read_b128 v[108:111], v59 offset:23104
	ds_read_b128 v[112:115], v58 offset:2624
	ds_read_b128 v[116:119], v58 offset:5184
	ds_read_b128 v[120:123], v58 offset:7744
	s_add_i32 s14, s6, 5
	s_add_i32 s22, s64, -1
	s_min_u32 s14, s14, s22
	s_lshl_b32 s22, s14, 7
	v_mfma_f32_16x16x32_bf16 v[30:33], v[176:179], v[180:183], v[30:33]
	v_mfma_f32_16x16x32_bf16 v[14:17], v[184:187], v[180:183], v[14:17]
	v_mfma_f32_16x16x32_bf16 v[26:29], v[176:179], v[188:191], v[26:29]
	v_mfma_f32_16x16x32_bf16 v[10:13], v[184:187], v[188:191], v[10:13]
	v_mfma_f32_16x16x32_bf16 v[22:25], v[176:179], v[192:195], v[22:25]
	v_mfma_f32_16x16x32_bf16 v[6:9], v[184:187], v[192:195], v[6:9]
	v_mfma_f32_16x16x32_bf16 v[18:21], v[176:179], v[196:199], v[18:21]
	v_mfma_f32_16x16x32_bf16 v[2:5], v[184:187], v[196:199], v[2:5]
	s_waitcnt lgkmcnt(12)
	v_lshl_add_u64 v[124:125], v[50:51], 0, s[22:23]
	v_lshl_add_u64 v[126:127], v[52:53], 0, s[22:23]
	global_load_dwordx4 v[84:87], v[124:125], off
	global_load_dwordx4 v[80:83], v[124:125], off offset:32
	global_load_dwordx4 v[76:79], v[126:127], off
	global_load_dwordx4 v[72:75], v[126:127], off offset:32
	v_mfma_f32_16x16x32_bf16 v[30:33], v[200:203], v[204:207], v[30:33]
	v_mfma_f32_16x16x32_bf16 v[14:17], v[208:211], v[204:207], v[14:17]
	v_mfma_f32_16x16x32_bf16 v[26:29], v[200:203], v[224:227], v[26:29]
	v_mfma_f32_16x16x32_bf16 v[10:13], v[208:211], v[224:227], v[10:13]
	v_mfma_f32_16x16x32_bf16 v[22:25], v[200:203], v[228:231], v[22:25]
	v_mfma_f32_16x16x32_bf16 v[6:9], v[208:211], v[228:231], v[6:9]
	v_mfma_f32_16x16x32_bf16 v[18:21], v[200:203], v[232:235], v[18:21]
	v_mfma_f32_16x16x32_bf16 v[2:5], v[208:211], v[232:235], v[2:5]
	s_waitcnt lgkmcnt(0)
	s_barrier
	s_add_i32 s6, s6, 2
	s_cmp_lt_u32 s6, s64
	s_cbranch_scc1 .Lsrt_loop
	s_waitcnt vmcnt(0)
